# in-proj RoPE cos/sin read from an LDS copy of the table (no vmcnt wait behind stores)
# baseline (speedup 1.0000x reference)
;     __host__ __device__ __forceinline__ bool next(int i, Unit& u) const { const long L = (long)i * G + cc; if (L >= nwg) return false; u.pm = (int)L / nN; u.pn = (int)L % nN; u.k0 = 0; u.nt = -1; u.flags = 0; return true; }
; #define PG8_STAGE(bufoff, gbase, voff) do { _Pragma("unroll") for (int _i = 0; _i < 2; ++_i) \
;         __builtin_amdgcn_global_load_lds((const unsigned*)((const char*)(gbase) + (voff)[_i]), (LAS unsigned*)(lds + (bufoff) + ldsw + _i * 8192), 16, 0, 0); } while (0)
; #define PG8_WAIT_V(n) asm volatile("s_waitcnt vmcnt(" #n ")" ::: "memory")
; #define PG8_BAR __builtin_amdgcn_s_barrier()
; template <class Epi, class Sched, bool ALIGN_EPI>
; __device__ __forceinline__ void gemm_phase(LAS unsigned char* lds, const Gemm g, const Sched& S, const Epi& E) {
;     ...
;     for (int i = 0; i < 2; ++i) { int R, C; stage_rc(tid * 16 + i * 8192, R, C);
;         const int Rb = Epi::PERM ? ((R & ~31) + perm32(R & 31)) : R;
;         voffA[i] = (unsigned)(R * g.lda + C) * 2u; voffB[i] = (unsigned)(Rb * g.ldb + C) * 2u; }
;     const size_t kstep = (size_t)(BK * 2);
;     const size_t hstepA = (size_t)HALF * g.lda * 2, hstepB = (size_t)HALF * g.ldb * 2;
;     const size_t tstepA = 2 * hstepA, tstepB = 2 * hstepB;
;     const unsigned ldsw = (unsigned)wid * 1024u;
;     const int aoff = lds_byte(wr * 64 + fr, fq * 8), boff = lds_byte(wc * 32 + fr, fq * 8);
;     ...
;     Unit cur, nxt; int ui = 0;
;     if (!S.next(0, cur)) return;
;     f32x4 acc[2][2][4][2];
; #pragma unroll
;     for (int a = 0; a < 2; ++a)
; #pragma unroll
;         for (int b = 0; b < 2; ++b)
; #pragma unroll
;             for (int m = 0; m < 4; ++m)
; #pragma unroll
;                 for (int n = 0; n < 2; ++n) acc[a][b][m][n] = (f32x4){0.f, 0.f, 0.f, 0.f};
;     bf16x8 At[4][2], B0[2][2], B1[2][2];
;     const char* cA = (const char*)g.A + (size_t)cur.pm * tstepA + (size_t)cur.pn * g.a_pn_off * 2 + (size_t)cur.k0 * 2; const char* cB = (const char*)g.Bt + (size_t)cur.pn * tstepB + (size_t)cur.k0 * 2;
;     PG8_STAGE(PG8_SB(0, 0), cB, voffB); PG8_STAGE(PG8_SB(0, 1), cB + hstepB, voffB); PG8_STAGE(PG8_SA(0, 0), cA, voffA); PG8_STAGE(PG8_SA(0, 1), cA + hstepA, voffA);
;     if (wr == 1) PG8_BAR;
;     PG8_WAIT_V(2); PG8_BAR;
;     PG8_STAGE(PG8_SB(1, 0), cB + kstep, voffB); PG8_STAGE(PG8_SA(1, 0), cA + kstep, voffA); PG8_STAGE(PG8_SB(1, 1), cB + hstepB + kstep, voffB);
.LBB0_232:
	s_or_b64 exec, exec, s[0:1]
	s_mov_b32 s73, s43
	v_readlane_b32 s4, v254, 0
	v_mov_b32_e32 v7, v192
	v_readlane_b32 s5, v254, 1
	v_writelane_b32 v255, s72, 36
	s_waitcnt lgkmcnt(0)
	s_barrier
	v_readlane_b32 s100, v252, 4
	v_readlane_b32 s101, v252, 5
	v_lshlrev_b32_e32 v12, 4, v192
	s_add_u32 s100, s100, 0x40c0000
	s_addc_u32 s101, s101, 0
	s_nop 3
	global_load_dwordx4 v[8:11], v12, s[100:101]
	v_add_u32_e32 v12, 0x20000, v12
	s_waitcnt vmcnt(0)
	ds_write_b128 v12, v[8:11]
	s_waitcnt lgkmcnt(0)
	s_and_b64 vcc, exec, s[4:5]
	v_readfirstlane_b32 s0, v7
	v_writelane_b32 v255, s73, 37
	s_cbranch_vccz .LBB0_616
	v_lshlrev_b32_e32 v0, 4, v7
	v_add_u32_e32 v1, 0x2000, v0
	v_ashrrev_i32_e32 v2, 31, v1
	v_lshrrev_b32_e32 v2, 22, v2
	v_add_u32_e32 v2, v1, v2
	v_ashrrev_i32_e32 v4, 10, v2
	v_mul_i32_i24_e32 v3, 0x400, v4
	v_sub_u32_e32 v1, v1, v3
	v_lshrrev_b32_e32 v3, 4, v1
	v_bitop3_b32 v1, v3, v1, 32 bitop3:0x6c
	v_ashrrev_i32_e32 v3, 31, v1
	v_lshrrev_b32_e32 v3, 26, v3
	v_add_u32_e32 v3, v1, v3
	v_ashrrev_i32_e32 v5, 6, v3
	v_and_b32_e32 v3, 0xc0, v3
	v_sub_u32_e32 v1, v1, v3
	v_lshlrev_b32_e32 v2, 5, v4
	v_ashrrev_i16_sdwa v1, v196, sext(v1) dst_sel:DWORD dst_unused:UNUSED_PAD src0_sel:DWORD src1_sel:BYTE_0
	v_and_b32_e32 v2, 32, v2
	v_bfe_i32 v6, v1, 0, 16
	v_add_u32_e32 v1, v2, v6
	v_lshlrev_b32_e32 v2, 3, v4
	v_and_b32_e32 v2, 0x1ffff0, v2
	v_add_lshl_u32 v2, v5, v2, 11
	v_lshl_add_u32 v146, v1, 1, v2
	v_bfe_i32 v2, v7, 27, 1
	v_lshrrev_b32_e32 v2, 22, v2
	v_add_u32_e32 v2, v0, v2
	v_and_b32_e32 v2, 0xfffffc00, v2
	v_sub_u32_e32 v0, v0, v2
	v_lshrrev_b32_e32 v2, 4, v0
	v_bitop3_b32 v2, v2, v0, 32 bitop3:0x6c
	v_ashrrev_i32_e32 v0, 31, v0
	v_lshrrev_b32_e32 v0, 26, v0
	v_ashrrev_i32_e32 v1, 31, v7
	v_add_u32_e32 v0, v2, v0
	v_lshrrev_b32_e32 v1, 26, v1
	v_ashrrev_i32_e32 v9, 6, v0
	v_readlane_b32 s4, v252, 0
	v_add_u32_e32 v1, v7, v1
	v_mul_i32_i24_e32 v0, 64, v9
	s_mul_i32 s1, s72, 0x500000
	v_readlane_b32 s8, v252, 4
	v_ashrrev_i32_e32 v8, 6, v1
	v_sub_u32_e32 v0, v2, v0
	v_readlane_b32 s9, v252, 5
	s_add_u32 s30, s8, s1
	v_lshlrev_b32_e32 v1, 5, v8
	v_ashrrev_i16_sdwa v0, v196, sext(v0) dst_sel:DWORD dst_unused:UNUSED_PAD src0_sel:DWORD src1_sel:BYTE_0
	v_readlane_b32 s6, v252, 2
	v_readlane_b32 s7, v252, 3
	s_addc_u32 s31, s9, 0
	s_ashr_i32 s4, s0, 6
	v_and_b32_e32 v1, 32, v1
	v_bfe_i32 v10, v0, 0, 16
	s_ashr_i32 s1, s0, 8
	s_lshl_b32 s38, s4, 10
	v_add_u32_e32 v0, v1, v10
	v_lshlrev_b32_e32 v1, 3, v8
	v_readlane_b32 s6, v254, 47
	v_and_b32_e32 v1, 0x1ffff0, v1
	v_readlane_b32 s7, v254, 48
	s_add_u32 s6, s30, s6
	v_add_lshl_u32 v1, v9, v1, 11
	s_addc_u32 s7, s31, s7
	s_add_i32 s39, s38, 0
	v_lshl_add_u32 v148, v0, 1, v1
	s_add_i32 m0, s39, 0x10000
	v_mov_b32_e32 v149, v161
	global_load_lds_dwordx4 v148, s[6:7]
	s_add_i32 m0, s39, 0x12000
	s_add_u32 s8, s6, 0x40000
	global_load_lds_dwordx4 v146, s[6:7]
	s_addc_u32 s9, s7, 0
	s_add_i32 m0, s39, 0x14000
	s_add_i32 s40, s39, 0x2000
	global_load_lds_dwordx4 v148, s[8:9]
	s_add_i32 m0, s39, 0x16000
	s_add_i32 s41, s39, 0x4000
	global_load_lds_dwordx4 v146, s[8:9]
	v_readlane_b32 s8, v254, 51
	s_mov_b32 m0, s39
	v_readlane_b32 s9, v254, 52
	s_add_i32 s75, s39, 0x6000
	v_mov_b32_e32 v147, v161
	s_cmp_eq_u32 s1, 1
	v_lshl_add_u64 v[0:1], s[6:7], 0, v[148:149]
	s_cselect_b64 s[46:47], -1, 0
	global_load_lds_dwordx4 v148, s[8:9]
	s_mov_b32 m0, s40
	s_cmp_lg_u32 s1, 1
	global_load_lds_dwordx4 v146, s[8:9]
	v_readlane_b32 s8, v254, 53
	s_mov_b32 m0, s41
	v_readlane_b32 s9, v254, 54
	v_lshl_add_u64 v[2:3], s[6:7], 0, v[146:147]
	v_readlane_b32 s5, v252, 1
	v_readlane_b32 s10, v252, 6
	v_readlane_b32 s11, v252, 7
	s_nop 0
	global_load_lds_dwordx4 v148, s[8:9]
	s_mov_b32 m0, s75
	s_nop 0
	global_load_lds_dwordx4 v146, s[8:9]
	s_cbranch_scc1 .LBB0_235
	s_barrier

; __device__ __forceinline__ u32x2 pack4(f32x4 v) { u32x2 w; w.x = cvt_pk_bf16(v[0], v[1]); w.y = cvt_pk_bf16(v[2], v[3]); return w; }
;     __device__ __forceinline__ void operator()(const Acc& acc, const pg8::Unit& u, int wr, int wc, int fr, int fq) const {
;     ...
;                     const int ax = fq >> 1, fh = fq & 1;
;                     u32x4 w1, w2;
; #pragma unroll
;                     for (int bj = 0; bj < 2; ++bj) {
;                         f32x4 cs = {1.f, 1.f, 1.f, 1.f}, sn = {0.f, 0.f, 0.f, 0.f};
;                         if (lat) { const int pidx = ax ? (t & 63) : (t >> 6); cs = *(const f32x4*)(rope + pidx * 16 + 8 * fh + 4 * bj); sn = *(const f32x4*)(rope + 1024 + pidx * 16 + 8 * fh + 4 * bj); }
;                         const f32x4 x1 = acc[ai][bj][m][0], x2 = acc[ai][bj][m][1];
;                         const u32x2 p1 = pack4((x1 * cs - x2 * sn) * scale), p2 = pack4((x2 * cs + x1 * sn) * scale);
;                         if (bj == 0) { w1.x = p1.x; w1.y = p1.y; w2.x = p2.x; w2.y = p2.y; } else { w1.z = p1.x; w1.w = p1.y; w2.z = p2.x; w2.w = p2.y; }
;                     }
;                     bf16_t* dq = dst + wc * 64 + ax * 32 + 8 * fh;
;                     *(u32x4*)dq = w1; *(u32x4*)(dq + 16) = w2;
.LBB0_279:
	v_lshrrev_b32_e32 v128, 6, v136
	v_cndmask_b32_e64 v128, v151, v128, s[14:15]
	v_lshlrev_b32_e32 v128, 6, v128
	v_mov_b32_e32 v129, v161
	v_lshl_add_u64 v[186:187], v[172:173], 0, v[128:129]
	v_subrev_u32_e32 v186, s100, v186
	v_add_u32_e32 v186, 0x20000, v186
	v_lshl_add_u64 v[188:189], v[174:175], 0, v[128:129]
	v_cndmask_b32_e64 v129, 0, 1, s[6:7]
	v_mov_b32_e32 v128, 1.0
	v_mov_b32_e32 v132, 0
	v_cmp_ne_u32_e64 s[0:1], 1, v129
	s_andn2_b64 vcc, exec, s[6:7]
	v_mov_b32_e32 v138, 0
	v_mov_b32_e32 v139, 0
	v_mov_b32_e32 v140, 0
	v_mov_b32_e32 v141, 0
	v_mov_b32_e32 v142, 1.0
	v_mov_b32_e32 v143, 1.0
	v_mov_b32_e32 v144, 1.0
	v_mov_b32_e32 v145, 1.0
	s_cbranch_vccnz .LBB0_281
	ds_read_b128 v[142:145], v186
	ds_read_b128 v[138:141], v186 offset:4096
.LBB0_281:
	s_waitcnt lgkmcnt(0)
	v_pk_mul_f32 v[130:131], v[122:123], v[140:141]
	v_pk_mul_f32 v[134:135], v[120:121], v[138:139]
	v_pk_fma_f32 v[130:131], v[126:127], v[144:145], v[130:131] neg_lo:[0,0,1] neg_hi:[0,0,1]
	v_pk_fma_f32 v[134:135], v[124:125], v[142:143], v[134:135] neg_lo:[0,0,1] neg_hi:[0,0,1]
	v_mov_b32_e32 v190, v180
	v_mov_b32_e32 v191, v180
	v_pk_mul_f32 v[120:121], v[120:121], v[142:143]
	v_pk_mul_f32 v[130:131], v[190:191], v[130:131]
	v_pk_mul_f32 v[134:135], v[180:181], v[134:135]
	v_pk_mul_f32 v[122:123], v[122:123], v[144:145]
	v_pk_fma_f32 v[120:121], v[124:125], v[138:139], v[120:121]
	v_cvt_pk_bf16_f32 v136, v134, v135
	v_cvt_pk_bf16_f32 v137, v130, v131
	v_pk_fma_f32 v[122:123], v[126:127], v[140:141], v[122:123]
	v_pk_mul_f32 v[120:121], v[180:181], v[120:121]
	s_and_b64 vcc, exec, s[0:1]
	v_mov_b32_e32 v133, 0
	v_mov_b32_e32 v134, 0
	v_mov_b32_e32 v135, 0
	v_mov_b32_e32 v129, 1.0
	v_mov_b32_e32 v130, 1.0
	v_mov_b32_e32 v131, 1.0
	v_pk_mul_f32 v[122:123], v[190:191], v[122:123]
	v_cvt_pk_bf16_f32 v120, v120, v121
	s_nop 0
	v_cvt_pk_bf16_f32 v121, v122, v123
	s_cbranch_vccnz .LBB0_283
	ds_read_b128 v[128:131], v186 offset:16
	ds_read_b128 v[132:135], v186 offset:4112
.LBB0_283:
	v_lshlrev_b64 v[122:123], 9, v[184:185]
	v_lshl_add_u64 v[124:125], s[8:9], 0, v[122:123]
	s_waitcnt lgkmcnt(0)
	v_pk_mul_f32 v[122:123], v[114:115], v[134:135]
	v_pk_mul_f32 v[126:127], v[112:113], v[132:133]
	v_pk_mul_f32 v[114:115], v[114:115], v[130:131]
	v_pk_mul_f32 v[112:113], v[112:113], v[128:129]
	v_pk_fma_f32 v[122:123], v[118:119], v[130:131], v[122:123] neg_lo:[0,0,1] neg_hi:[0,0,1]
	v_pk_fma_f32 v[112:113], v[116:117], v[132:133], v[112:113]
	v_pk_fma_f32 v[114:115], v[118:119], v[134:135], v[114:115]
	v_pk_mul_f32 v[122:123], v[190:191], v[122:123]
	v_pk_mul_f32 v[114:115], v[190:191], v[114:115]
	v_pk_mul_f32 v[112:113], v[180:181], v[112:113]
	s_lshl_b32 s0, s53, 1
	s_mov_b32 s1, s43
	v_cvt_pk_bf16_f32 v139, v122, v123
	v_cvt_pk_bf16_f32 v122, v112, v113
	v_cvt_pk_bf16_f32 v123, v114, v115
	v_lshl_add_u64 v[112:113], v[124:125], 0, s[0:1]
	v_lshlrev_b32_e32 v114, 1, v156
	v_mov_b32_e32 v115, v161
	v_pk_fma_f32 v[126:127], v[116:117], v[128:129], v[126:127] neg_lo:[0,0,1] neg_hi:[0,0,1]
	v_lshl_add_u64 v[112:113], v[112:113], 0, v[114:115]
	v_lshlrev_b32_e32 v114, 1, v154
	v_pk_mul_f32 v[126:127], v[180:181], v[126:127]
	v_lshl_add_u64 v[112:113], v[112:113], 0, v[114:115]
	v_cvt_pk_bf16_f32 v138, v126, v127
	global_store_dwordx4 v[112:113], v[136:139], off
	global_store_dwordx4 v[112:113], v[120:123], off offset:32

; __device__ __forceinline__ u32x2 pack4(f32x4 v) { u32x2 w; w.x = cvt_pk_bf16(v[0], v[1]); w.y = cvt_pk_bf16(v[2], v[3]); return w; }
;     __device__ __forceinline__ void operator()(const Acc& acc, const pg8::Unit& u, int wr, int wc, int fr, int fq) const {
;     ...
;                     const int ax = fq >> 1, fh = fq & 1;
;                     u32x4 w1, w2;
; #pragma unroll
;                     for (int bj = 0; bj < 2; ++bj) {
;                         f32x4 cs = {1.f, 1.f, 1.f, 1.f}, sn = {0.f, 0.f, 0.f, 0.f};
;                         if (lat) { const int pidx = ax ? (t & 63) : (t >> 6); cs = *(const f32x4*)(rope + pidx * 16 + 8 * fh + 4 * bj); sn = *(const f32x4*)(rope + 1024 + pidx * 16 + 8 * fh + 4 * bj); }
;                         const f32x4 x1 = acc[ai][bj][m][0], x2 = acc[ai][bj][m][1];
;                         const u32x2 p1 = pack4((x1 * cs - x2 * sn) * scale), p2 = pack4((x2 * cs + x1 * sn) * scale);
;                         if (bj == 0) { w1.x = p1.x; w1.y = p1.y; w2.x = p2.x; w2.y = p2.y; } else { w1.z = p1.x; w1.w = p1.y; w2.z = p2.x; w2.w = p2.y; }
;                     }
;                     bf16_t* dq = dst + wc * 64 + ax * 32 + 8 * fh;
;                     *(u32x4*)dq = w1; *(u32x4*)(dq + 16) = w2;
.LBB0_319:
	v_lshrrev_b32_e32 v112, 6, v122
	v_cndmask_b32_e64 v112, v155, v112, s[14:15]
	v_lshlrev_b32_e32 v112, 6, v112
	v_mov_b32_e32 v113, v161
	v_lshl_add_u64 v[132:133], v[172:173], 0, v[112:113]
	v_subrev_u32_e32 v132, s100, v132
	v_add_u32_e32 v132, 0x20000, v132
	v_lshl_add_u64 v[134:135], v[174:175], 0, v[112:113]
	v_cndmask_b32_e64 v113, 0, 1, s[6:7]
	v_mov_b32_e32 v112, 1.0
	v_mov_b32_e32 v116, 0
	v_cmp_ne_u32_e64 s[0:1], 1, v113
	s_andn2_b64 vcc, exec, s[6:7]
	v_mov_b32_e32 v122, 0
	v_mov_b32_e32 v123, 0
	v_mov_b32_e32 v124, 0
	v_mov_b32_e32 v125, 0
	v_mov_b32_e32 v126, 1.0
	v_mov_b32_e32 v127, 1.0
	v_mov_b32_e32 v128, 1.0
	v_mov_b32_e32 v129, 1.0
	s_cbranch_vccnz .LBB0_321
	ds_read_b128 v[126:129], v132
	ds_read_b128 v[122:125], v132 offset:4096
.LBB0_321:
	s_waitcnt lgkmcnt(0)
	v_pk_mul_f32 v[114:115], v[106:107], v[124:125]
	v_pk_mul_f32 v[118:119], v[104:105], v[122:123]
	v_pk_fma_f32 v[114:115], v[110:111], v[128:129], v[114:115] neg_lo:[0,0,1] neg_hi:[0,0,1]
	v_pk_fma_f32 v[118:119], v[108:109], v[126:127], v[118:119] neg_lo:[0,0,1] neg_hi:[0,0,1]
	v_mov_b32_e32 v136, v180
	v_mov_b32_e32 v137, v180
	v_pk_mul_f32 v[104:105], v[104:105], v[126:127]
	v_pk_mul_f32 v[114:115], v[136:137], v[114:115]
	v_pk_mul_f32 v[118:119], v[180:181], v[118:119]
	v_pk_mul_f32 v[106:107], v[106:107], v[128:129]
	v_pk_fma_f32 v[104:105], v[108:109], v[122:123], v[104:105]
	v_cvt_pk_bf16_f32 v120, v118, v119
	v_cvt_pk_bf16_f32 v121, v114, v115
	v_pk_fma_f32 v[106:107], v[110:111], v[124:125], v[106:107]
	v_pk_mul_f32 v[104:105], v[180:181], v[104:105]
	s_and_b64 vcc, exec, s[0:1]
	v_mov_b32_e32 v117, 0
	v_mov_b32_e32 v118, 0
	v_mov_b32_e32 v119, 0
	v_mov_b32_e32 v113, 1.0
	v_mov_b32_e32 v114, 1.0
	v_mov_b32_e32 v115, 1.0
	v_pk_mul_f32 v[106:107], v[136:137], v[106:107]
	v_cvt_pk_bf16_f32 v104, v104, v105
	s_nop 0
	v_cvt_pk_bf16_f32 v105, v106, v107
	s_cbranch_vccnz .LBB0_323
	ds_read_b128 v[112:115], v132 offset:16
	ds_read_b128 v[116:119], v132 offset:4112
.LBB0_323:
	v_lshlrev_b64 v[106:107], 9, v[130:131]
	v_lshl_add_u64 v[108:109], s[12:13], 0, v[106:107]
	s_waitcnt lgkmcnt(0)
	v_pk_mul_f32 v[106:107], v[98:99], v[118:119]
	v_pk_mul_f32 v[110:111], v[96:97], v[116:117]
	v_pk_mul_f32 v[98:99], v[98:99], v[114:115]
	v_pk_mul_f32 v[96:97], v[96:97], v[112:113]
	v_pk_fma_f32 v[106:107], v[102:103], v[114:115], v[106:107] neg_lo:[0,0,1] neg_hi:[0,0,1]
	v_pk_fma_f32 v[96:97], v[100:101], v[116:117], v[96:97]
	v_pk_fma_f32 v[98:99], v[102:103], v[118:119], v[98:99]
	v_pk_mul_f32 v[106:107], v[136:137], v[106:107]
	v_pk_mul_f32 v[98:99], v[136:137], v[98:99]
	v_pk_mul_f32 v[96:97], v[180:181], v[96:97]
	s_lshl_b32 s0, s53, 1
	s_mov_b32 s1, s43
	v_cvt_pk_bf16_f32 v123, v106, v107
	v_cvt_pk_bf16_f32 v106, v96, v97
	v_cvt_pk_bf16_f32 v107, v98, v99
	v_lshl_add_u64 v[96:97], v[108:109], 0, s[0:1]
	v_lshlrev_b32_e32 v98, 1, v156
	v_mov_b32_e32 v99, v161
	v_pk_fma_f32 v[110:111], v[100:101], v[112:113], v[110:111] neg_lo:[0,0,1] neg_hi:[0,0,1]
	v_lshl_add_u64 v[96:97], v[96:97], 0, v[98:99]
	v_lshlrev_b32_e32 v98, 1, v154
	v_pk_mul_f32 v[110:111], v[180:181], v[110:111]
	v_lshl_add_u64 v[96:97], v[96:97], 0, v[98:99]
	v_cvt_pk_bf16_f32 v122, v110, v111
	global_store_dwordx4 v[96:97], v[120:123], off
	global_store_dwordx4 v[96:97], v[104:107], off offset:32

; __device__ __forceinline__ u32x2 pack4(f32x4 v) { u32x2 w; w.x = cvt_pk_bf16(v[0], v[1]); w.y = cvt_pk_bf16(v[2], v[3]); return w; }
;     __device__ __forceinline__ void operator()(const Acc& acc, const pg8::Unit& u, int wr, int wc, int fr, int fq) const {
;     ...
;                     const int ax = fq >> 1, fh = fq & 1;
;                     u32x4 w1, w2;
; #pragma unroll
;                     for (int bj = 0; bj < 2; ++bj) {
;                         f32x4 cs = {1.f, 1.f, 1.f, 1.f}, sn = {0.f, 0.f, 0.f, 0.f};
;                         if (lat) { const int pidx = ax ? (t & 63) : (t >> 6); cs = *(const f32x4*)(rope + pidx * 16 + 8 * fh + 4 * bj); sn = *(const f32x4*)(rope + 1024 + pidx * 16 + 8 * fh + 4 * bj); }
;                         const f32x4 x1 = acc[ai][bj][m][0], x2 = acc[ai][bj][m][1];
;                         const u32x2 p1 = pack4((x1 * cs - x2 * sn) * scale), p2 = pack4((x2 * cs + x1 * sn) * scale);
;                         if (bj == 0) { w1.x = p1.x; w1.y = p1.y; w2.x = p2.x; w2.y = p2.y; } else { w1.z = p1.x; w1.w = p1.y; w2.z = p2.x; w2.w = p2.y; }
;                     }
;                     bf16_t* dq = dst + wc * 64 + ax * 32 + 8 * fh;
;                     *(u32x4*)dq = w1; *(u32x4*)(dq + 16) = w2;
.LBB0_359:
	v_lshrrev_b32_e32 v96, 6, v106
	v_cndmask_b32_e64 v96, v157, v96, s[14:15]
	v_lshlrev_b32_e32 v96, 6, v96
	v_mov_b32_e32 v97, v161
	v_lshl_add_u64 v[116:117], v[172:173], 0, v[96:97]
	v_subrev_u32_e32 v116, s100, v116
	v_add_u32_e32 v116, 0x20000, v116
	v_lshl_add_u64 v[118:119], v[174:175], 0, v[96:97]
	v_cndmask_b32_e64 v97, 0, 1, s[6:7]
	v_mov_b32_e32 v96, 1.0
	v_mov_b32_e32 v100, 0
	v_cmp_ne_u32_e64 s[0:1], 1, v97
	s_andn2_b64 vcc, exec, s[6:7]
	v_mov_b32_e32 v106, 0
	v_mov_b32_e32 v107, 0
	v_mov_b32_e32 v108, 0
	v_mov_b32_e32 v109, 0
	v_mov_b32_e32 v110, 1.0
	v_mov_b32_e32 v111, 1.0
	v_mov_b32_e32 v112, 1.0
	v_mov_b32_e32 v113, 1.0
	s_cbranch_vccnz .LBB0_361
	ds_read_b128 v[110:113], v116
	ds_read_b128 v[106:109], v116 offset:4096
.LBB0_361:
	s_waitcnt lgkmcnt(0)
	v_pk_mul_f32 v[98:99], v[90:91], v[108:109]
	v_pk_mul_f32 v[102:103], v[88:89], v[106:107]
	v_pk_fma_f32 v[98:99], v[94:95], v[112:113], v[98:99] neg_lo:[0,0,1] neg_hi:[0,0,1]
	v_pk_fma_f32 v[102:103], v[92:93], v[110:111], v[102:103] neg_lo:[0,0,1] neg_hi:[0,0,1]
	v_mov_b32_e32 v120, v180
	v_mov_b32_e32 v121, v180
	v_pk_mul_f32 v[88:89], v[88:89], v[110:111]
	v_pk_mul_f32 v[98:99], v[120:121], v[98:99]
	v_pk_mul_f32 v[102:103], v[180:181], v[102:103]
	v_pk_mul_f32 v[90:91], v[90:91], v[112:113]
	v_pk_fma_f32 v[88:89], v[92:93], v[106:107], v[88:89]
	v_cvt_pk_bf16_f32 v104, v102, v103
	v_cvt_pk_bf16_f32 v105, v98, v99
	v_pk_fma_f32 v[90:91], v[94:95], v[108:109], v[90:91]
	v_pk_mul_f32 v[88:89], v[180:181], v[88:89]
	s_and_b64 vcc, exec, s[0:1]
	v_mov_b32_e32 v101, 0
	v_mov_b32_e32 v102, 0
	v_mov_b32_e32 v103, 0
	v_mov_b32_e32 v97, 1.0
	v_mov_b32_e32 v98, 1.0
	v_mov_b32_e32 v99, 1.0
	v_pk_mul_f32 v[90:91], v[120:121], v[90:91]
	v_cvt_pk_bf16_f32 v88, v88, v89
	s_nop 0
	v_cvt_pk_bf16_f32 v89, v90, v91
	s_cbranch_vccnz .LBB0_363
	ds_read_b128 v[96:99], v116 offset:16
	ds_read_b128 v[100:103], v116 offset:4112
.LBB0_363:
	v_lshlrev_b64 v[90:91], 9, v[114:115]
	v_lshl_add_u64 v[92:93], s[12:13], 0, v[90:91]
	s_waitcnt lgkmcnt(0)
	v_pk_mul_f32 v[90:91], v[82:83], v[102:103]
	v_pk_mul_f32 v[94:95], v[80:81], v[100:101]
	v_pk_mul_f32 v[82:83], v[82:83], v[98:99]
	v_pk_mul_f32 v[80:81], v[80:81], v[96:97]
	v_pk_fma_f32 v[90:91], v[86:87], v[98:99], v[90:91] neg_lo:[0,0,1] neg_hi:[0,0,1]
	v_pk_fma_f32 v[80:81], v[84:85], v[100:101], v[80:81]
	v_pk_fma_f32 v[82:83], v[86:87], v[102:103], v[82:83]
	v_pk_mul_f32 v[90:91], v[120:121], v[90:91]
	v_pk_mul_f32 v[82:83], v[120:121], v[82:83]
	v_pk_mul_f32 v[80:81], v[180:181], v[80:81]
	s_lshl_b32 s0, s53, 1
	s_mov_b32 s1, s43
	v_cvt_pk_bf16_f32 v107, v90, v91
	v_cvt_pk_bf16_f32 v90, v80, v81
	v_cvt_pk_bf16_f32 v91, v82, v83
	v_lshl_add_u64 v[80:81], v[92:93], 0, s[0:1]
	v_lshlrev_b32_e32 v82, 1, v156
	v_mov_b32_e32 v83, v161
	v_pk_fma_f32 v[94:95], v[84:85], v[96:97], v[94:95] neg_lo:[0,0,1] neg_hi:[0,0,1]
	v_lshl_add_u64 v[80:81], v[80:81], 0, v[82:83]
	v_lshlrev_b32_e32 v82, 1, v154
	v_pk_mul_f32 v[94:95], v[180:181], v[94:95]
	v_lshl_add_u64 v[80:81], v[80:81], 0, v[82:83]
	v_cvt_pk_bf16_f32 v106, v94, v95
	global_store_dwordx4 v[80:81], v[104:107], off
	global_store_dwordx4 v[80:81], v[88:91], off offset:32

; __device__ __forceinline__ u32x2 pack4(f32x4 v) { u32x2 w; w.x = cvt_pk_bf16(v[0], v[1]); w.y = cvt_pk_bf16(v[2], v[3]); return w; }
;     __device__ __forceinline__ void operator()(const Acc& acc, const pg8::Unit& u, int wr, int wc, int fr, int fq) const {
;     ...
;                     const int ax = fq >> 1, fh = fq & 1;
;                     u32x4 w1, w2;
; #pragma unroll
;                     for (int bj = 0; bj < 2; ++bj) {
;                         f32x4 cs = {1.f, 1.f, 1.f, 1.f}, sn = {0.f, 0.f, 0.f, 0.f};
;                         if (lat) { const int pidx = ax ? (t & 63) : (t >> 6); cs = *(const f32x4*)(rope + pidx * 16 + 8 * fh + 4 * bj); sn = *(const f32x4*)(rope + 1024 + pidx * 16 + 8 * fh + 4 * bj); }
;                         const f32x4 x1 = acc[ai][bj][m][0], x2 = acc[ai][bj][m][1];
;                         const u32x2 p1 = pack4((x1 * cs - x2 * sn) * scale), p2 = pack4((x2 * cs + x1 * sn) * scale);
;                         if (bj == 0) { w1.x = p1.x; w1.y = p1.y; w2.x = p2.x; w2.y = p2.y; } else { w1.z = p1.x; w1.w = p1.y; w2.z = p2.x; w2.w = p2.y; }
;                     }
;                     bf16_t* dq = dst + wc * 64 + ax * 32 + 8 * fh;
;                     *(u32x4*)dq = w1; *(u32x4*)(dq + 16) = w2;
.LBB0_399:
	v_lshrrev_b32_e32 v80, 6, v90
	v_cndmask_b32_e64 v80, v159, v80, s[14:15]
	v_lshlrev_b32_e32 v80, 6, v80
	v_mov_b32_e32 v81, v161
	v_lshl_add_u64 v[100:101], v[172:173], 0, v[80:81]
	v_subrev_u32_e32 v100, s100, v100
	v_add_u32_e32 v100, 0x20000, v100
	v_lshl_add_u64 v[102:103], v[174:175], 0, v[80:81]
	v_cndmask_b32_e64 v81, 0, 1, s[6:7]
	v_mov_b32_e32 v80, 1.0
	v_mov_b32_e32 v84, 0
	v_cmp_ne_u32_e64 s[0:1], 1, v81
	s_andn2_b64 vcc, exec, s[6:7]
	v_mov_b32_e32 v90, 0
	v_mov_b32_e32 v91, 0
	v_mov_b32_e32 v92, 0
	v_mov_b32_e32 v93, 0
	v_mov_b32_e32 v94, 1.0
	v_mov_b32_e32 v95, 1.0
	v_mov_b32_e32 v96, 1.0
	v_mov_b32_e32 v97, 1.0
	s_cbranch_vccnz .LBB0_401
	ds_read_b128 v[94:97], v100
	ds_read_b128 v[90:93], v100 offset:4096
.LBB0_401:
	s_waitcnt lgkmcnt(0)
	v_pk_mul_f32 v[82:83], v[74:75], v[92:93]
	v_pk_mul_f32 v[86:87], v[72:73], v[90:91]
	v_pk_fma_f32 v[82:83], v[78:79], v[96:97], v[82:83] neg_lo:[0,0,1] neg_hi:[0,0,1]
	v_pk_fma_f32 v[86:87], v[76:77], v[94:95], v[86:87] neg_lo:[0,0,1] neg_hi:[0,0,1]
	v_mov_b32_e32 v104, v180
	v_mov_b32_e32 v105, v180
	v_pk_mul_f32 v[72:73], v[72:73], v[94:95]
	v_pk_mul_f32 v[82:83], v[104:105], v[82:83]
	v_pk_mul_f32 v[86:87], v[180:181], v[86:87]
	v_pk_mul_f32 v[74:75], v[74:75], v[96:97]
	v_pk_fma_f32 v[72:73], v[76:77], v[90:91], v[72:73]
	v_cvt_pk_bf16_f32 v88, v86, v87
	v_cvt_pk_bf16_f32 v89, v82, v83
	v_pk_fma_f32 v[74:75], v[78:79], v[92:93], v[74:75]
	v_pk_mul_f32 v[72:73], v[180:181], v[72:73]
	s_and_b64 vcc, exec, s[0:1]
	v_mov_b32_e32 v85, 0
	v_mov_b32_e32 v86, 0
	v_mov_b32_e32 v87, 0
	v_mov_b32_e32 v81, 1.0
	v_mov_b32_e32 v82, 1.0
	v_mov_b32_e32 v83, 1.0
	v_pk_mul_f32 v[74:75], v[104:105], v[74:75]
	v_cvt_pk_bf16_f32 v72, v72, v73
	s_nop 0
	v_cvt_pk_bf16_f32 v73, v74, v75
	s_cbranch_vccnz .LBB0_403
	ds_read_b128 v[80:83], v100 offset:16
	ds_read_b128 v[84:87], v100 offset:4112
.LBB0_403:
	v_lshlrev_b64 v[74:75], 9, v[98:99]
	v_lshl_add_u64 v[76:77], s[12:13], 0, v[74:75]
	s_waitcnt lgkmcnt(0)
	v_pk_mul_f32 v[74:75], v[66:67], v[86:87]
	v_pk_mul_f32 v[78:79], v[64:65], v[84:85]
	v_pk_mul_f32 v[66:67], v[66:67], v[82:83]
	v_pk_mul_f32 v[64:65], v[64:65], v[80:81]
	v_pk_fma_f32 v[74:75], v[70:71], v[82:83], v[74:75] neg_lo:[0,0,1] neg_hi:[0,0,1]
	v_pk_fma_f32 v[64:65], v[68:69], v[84:85], v[64:65]
	v_pk_fma_f32 v[66:67], v[70:71], v[86:87], v[66:67]
	v_pk_mul_f32 v[74:75], v[104:105], v[74:75]
	v_pk_mul_f32 v[66:67], v[104:105], v[66:67]
	v_pk_mul_f32 v[64:65], v[180:181], v[64:65]
	s_lshl_b32 s0, s53, 1
	s_mov_b32 s1, s43
	v_cvt_pk_bf16_f32 v91, v74, v75
	v_cvt_pk_bf16_f32 v74, v64, v65
	v_cvt_pk_bf16_f32 v75, v66, v67
	v_lshl_add_u64 v[64:65], v[76:77], 0, s[0:1]
	v_lshlrev_b32_e32 v66, 1, v156
	v_mov_b32_e32 v67, v161
	v_pk_fma_f32 v[78:79], v[68:69], v[80:81], v[78:79] neg_lo:[0,0,1] neg_hi:[0,0,1]
	v_lshl_add_u64 v[64:65], v[64:65], 0, v[66:67]
	v_lshlrev_b32_e32 v66, 1, v154
	v_pk_mul_f32 v[78:79], v[180:181], v[78:79]
	v_lshl_add_u64 v[64:65], v[64:65], 0, v[66:67]
	v_cvt_pk_bf16_f32 v90, v78, v79
	global_store_dwordx4 v[64:65], v[88:91], off
	global_store_dwordx4 v[64:65], v[72:75], off offset:32

; __device__ __forceinline__ u32x2 pack4(f32x4 v) { u32x2 w; w.x = cvt_pk_bf16(v[0], v[1]); w.y = cvt_pk_bf16(v[2], v[3]); return w; }
;     __device__ __forceinline__ void operator()(const Acc& acc, const pg8::Unit& u, int wr, int wc, int fr, int fq) const {
;     ...
;                     const int ax = fq >> 1, fh = fq & 1;
;                     u32x4 w1, w2;
; #pragma unroll
;                     for (int bj = 0; bj < 2; ++bj) {
;                         f32x4 cs = {1.f, 1.f, 1.f, 1.f}, sn = {0.f, 0.f, 0.f, 0.f};
;                         if (lat) { const int pidx = ax ? (t & 63) : (t >> 6); cs = *(const f32x4*)(rope + pidx * 16 + 8 * fh + 4 * bj); sn = *(const f32x4*)(rope + 1024 + pidx * 16 + 8 * fh + 4 * bj); }
;                         const f32x4 x1 = acc[ai][bj][m][0], x2 = acc[ai][bj][m][1];
;                         const u32x2 p1 = pack4((x1 * cs - x2 * sn) * scale), p2 = pack4((x2 * cs + x1 * sn) * scale);
;                         if (bj == 0) { w1.x = p1.x; w1.y = p1.y; w2.x = p2.x; w2.y = p2.y; } else { w1.z = p1.x; w1.w = p1.y; w2.z = p2.x; w2.w = p2.y; }
;                     }
;                     bf16_t* dq = dst + wc * 64 + ax * 32 + 8 * fh;
;                     *(u32x4*)dq = w1; *(u32x4*)(dq + 16) = w2;
.LBB0_439:
	v_lshrrev_b32_e32 v64, 6, v72
	v_cndmask_b32_e64 v64, v151, v64, s[14:15]
	v_lshlrev_b32_e32 v64, 6, v64
	v_mov_b32_e32 v65, v161
	v_lshl_add_u64 v[86:87], v[172:173], 0, v[64:65]
	v_subrev_u32_e32 v86, s100, v86
	v_add_u32_e32 v86, 0x20000, v86
	v_lshl_add_u64 v[88:89], v[174:175], 0, v[64:65]
	v_cndmask_b32_e64 v65, 0, 1, s[6:7]
	v_mov_b32_e32 v64, 1.0
	v_mov_b32_e32 v68, 0
	v_cmp_ne_u32_e64 s[0:1], 1, v65
	s_andn2_b64 vcc, exec, s[6:7]
	v_mov_b32_e32 v74, 0
	v_mov_b32_e32 v75, 0
	v_mov_b32_e32 v76, 0
	v_mov_b32_e32 v77, 0
	v_mov_b32_e32 v78, 1.0
	v_mov_b32_e32 v79, 1.0
	v_mov_b32_e32 v80, 1.0
	v_mov_b32_e32 v81, 1.0
	s_cbranch_vccnz .LBB0_441
	ds_read_b128 v[78:81], v86
	ds_read_b128 v[74:77], v86 offset:4096
.LBB0_441:
	s_waitcnt lgkmcnt(0)
	v_pk_mul_f32 v[66:67], v[58:59], v[76:77]
	v_pk_mul_f32 v[70:71], v[56:57], v[74:75]
	v_pk_fma_f32 v[66:67], v[62:63], v[80:81], v[66:67] neg_lo:[0,0,1] neg_hi:[0,0,1]
	v_pk_fma_f32 v[70:71], v[60:61], v[78:79], v[70:71] neg_lo:[0,0,1] neg_hi:[0,0,1]
	v_mov_b32_e32 v90, v180
	v_mov_b32_e32 v91, v180
	v_pk_mul_f32 v[56:57], v[56:57], v[78:79]
	v_pk_mul_f32 v[66:67], v[90:91], v[66:67]
	v_pk_mul_f32 v[70:71], v[180:181], v[70:71]
	v_pk_mul_f32 v[58:59], v[58:59], v[80:81]
	v_pk_fma_f32 v[56:57], v[60:61], v[74:75], v[56:57]
	v_cvt_pk_bf16_f32 v72, v70, v71
	v_cvt_pk_bf16_f32 v73, v66, v67
	v_pk_fma_f32 v[58:59], v[62:63], v[76:77], v[58:59]
	v_pk_mul_f32 v[56:57], v[180:181], v[56:57]
	s_and_b64 vcc, exec, s[0:1]
	v_mov_b32_e32 v69, 0
	v_mov_b32_e32 v70, 0
	v_mov_b32_e32 v71, 0
	v_mov_b32_e32 v65, 1.0
	v_mov_b32_e32 v66, 1.0
	v_mov_b32_e32 v67, 1.0
	v_pk_mul_f32 v[58:59], v[90:91], v[58:59]
	v_cvt_pk_bf16_f32 v56, v56, v57
	s_nop 0
	v_cvt_pk_bf16_f32 v57, v58, v59
	s_cbranch_vccnz .LBB0_443
	ds_read_b128 v[64:67], v86 offset:16
	ds_read_b128 v[68:71], v86 offset:4112
.LBB0_443:
	v_lshlrev_b64 v[58:59], 9, v[84:85]
	v_lshl_add_u64 v[60:61], s[12:13], 0, v[58:59]
	s_waitcnt lgkmcnt(0)
	v_pk_mul_f32 v[58:59], v[50:51], v[70:71]
	v_pk_mul_f32 v[62:63], v[48:49], v[68:69]
	v_pk_mul_f32 v[50:51], v[50:51], v[66:67]
	v_pk_mul_f32 v[48:49], v[48:49], v[64:65]
	v_pk_fma_f32 v[58:59], v[54:55], v[66:67], v[58:59] neg_lo:[0,0,1] neg_hi:[0,0,1]
	v_pk_fma_f32 v[48:49], v[52:53], v[68:69], v[48:49]
	v_pk_fma_f32 v[50:51], v[54:55], v[70:71], v[50:51]
	v_pk_mul_f32 v[58:59], v[90:91], v[58:59]
	v_pk_mul_f32 v[50:51], v[90:91], v[50:51]
	v_pk_mul_f32 v[48:49], v[180:181], v[48:49]
	s_lshl_b32 s0, s53, 1
	s_mov_b32 s1, s43
	v_cvt_pk_bf16_f32 v75, v58, v59
	v_cvt_pk_bf16_f32 v58, v48, v49
	v_cvt_pk_bf16_f32 v59, v50, v51
	v_lshl_add_u64 v[48:49], v[60:61], 0, s[0:1]
	v_lshlrev_b32_e32 v50, 1, v156
	v_mov_b32_e32 v51, v161
	v_pk_fma_f32 v[62:63], v[52:53], v[64:65], v[62:63] neg_lo:[0,0,1] neg_hi:[0,0,1]
	v_lshl_add_u64 v[48:49], v[48:49], 0, v[50:51]
	v_lshlrev_b32_e32 v50, 1, v154
	v_pk_mul_f32 v[62:63], v[180:181], v[62:63]
	v_lshl_add_u64 v[48:49], v[48:49], 0, v[50:51]
	v_cvt_pk_bf16_f32 v74, v62, v63
	global_store_dwordx4 v[48:49], v[72:75], off
	global_store_dwordx4 v[48:49], v[56:59], off offset:32

; __device__ __forceinline__ u32x2 pack4(f32x4 v) { u32x2 w; w.x = cvt_pk_bf16(v[0], v[1]); w.y = cvt_pk_bf16(v[2], v[3]); return w; }
;     __device__ __forceinline__ void operator()(const Acc& acc, const pg8::Unit& u, int wr, int wc, int fr, int fq) const {
;     ...
;                     const int ax = fq >> 1, fh = fq & 1;
;                     u32x4 w1, w2;
; #pragma unroll
;                     for (int bj = 0; bj < 2; ++bj) {
;                         f32x4 cs = {1.f, 1.f, 1.f, 1.f}, sn = {0.f, 0.f, 0.f, 0.f};
;                         if (lat) { const int pidx = ax ? (t & 63) : (t >> 6); cs = *(const f32x4*)(rope + pidx * 16 + 8 * fh + 4 * bj); sn = *(const f32x4*)(rope + 1024 + pidx * 16 + 8 * fh + 4 * bj); }
;                         const f32x4 x1 = acc[ai][bj][m][0], x2 = acc[ai][bj][m][1];
;                         const u32x2 p1 = pack4((x1 * cs - x2 * sn) * scale), p2 = pack4((x2 * cs + x1 * sn) * scale);
;                         if (bj == 0) { w1.x = p1.x; w1.y = p1.y; w2.x = p2.x; w2.y = p2.y; } else { w1.z = p1.x; w1.w = p1.y; w2.z = p2.x; w2.w = p2.y; }
;                     }
;                     bf16_t* dq = dst + wc * 64 + ax * 32 + 8 * fh;
;                     *(u32x4*)dq = w1; *(u32x4*)(dq + 16) = w2;
.LBB0_479:
	v_lshrrev_b32_e32 v48, 6, v58
	v_cndmask_b32_e64 v48, v155, v48, s[14:15]
	v_lshlrev_b32_e32 v48, 6, v48
	v_mov_b32_e32 v49, v161
	v_lshl_add_u64 v[68:69], v[172:173], 0, v[48:49]
	v_subrev_u32_e32 v68, s100, v68
	v_add_u32_e32 v68, 0x20000, v68
	v_lshl_add_u64 v[70:71], v[174:175], 0, v[48:49]
	v_cndmask_b32_e64 v49, 0, 1, s[6:7]
	v_mov_b32_e32 v48, 1.0
	v_mov_b32_e32 v52, 0
	v_cmp_ne_u32_e64 s[0:1], 1, v49
	s_andn2_b64 vcc, exec, s[6:7]
	v_mov_b32_e32 v58, 0
	v_mov_b32_e32 v59, 0
	v_mov_b32_e32 v60, 0
	v_mov_b32_e32 v61, 0
	v_mov_b32_e32 v62, 1.0
	v_mov_b32_e32 v63, 1.0
	v_mov_b32_e32 v64, 1.0
	v_mov_b32_e32 v65, 1.0
	s_cbranch_vccnz .LBB0_481
	ds_read_b128 v[62:65], v68
	ds_read_b128 v[58:61], v68 offset:4096
.LBB0_481:
	s_waitcnt lgkmcnt(0)
	v_pk_mul_f32 v[50:51], v[42:43], v[60:61]
	v_pk_mul_f32 v[54:55], v[40:41], v[58:59]
	v_pk_fma_f32 v[50:51], v[46:47], v[64:65], v[50:51] neg_lo:[0,0,1] neg_hi:[0,0,1]
	v_pk_fma_f32 v[54:55], v[44:45], v[62:63], v[54:55] neg_lo:[0,0,1] neg_hi:[0,0,1]
	v_mov_b32_e32 v72, v180
	v_mov_b32_e32 v73, v180
	v_pk_mul_f32 v[40:41], v[40:41], v[62:63]
	v_pk_mul_f32 v[50:51], v[72:73], v[50:51]
	v_pk_mul_f32 v[54:55], v[180:181], v[54:55]
	v_pk_mul_f32 v[42:43], v[42:43], v[64:65]
	v_pk_fma_f32 v[40:41], v[44:45], v[58:59], v[40:41]
	v_cvt_pk_bf16_f32 v56, v54, v55
	v_cvt_pk_bf16_f32 v57, v50, v51
	v_pk_fma_f32 v[42:43], v[46:47], v[60:61], v[42:43]
	v_pk_mul_f32 v[40:41], v[180:181], v[40:41]
	s_and_b64 vcc, exec, s[0:1]
	v_mov_b32_e32 v53, 0
	v_mov_b32_e32 v54, 0
	v_mov_b32_e32 v55, 0
	v_mov_b32_e32 v49, 1.0
	v_mov_b32_e32 v50, 1.0
	v_mov_b32_e32 v51, 1.0
	v_pk_mul_f32 v[42:43], v[72:73], v[42:43]
	v_cvt_pk_bf16_f32 v40, v40, v41
	s_nop 0
	v_cvt_pk_bf16_f32 v41, v42, v43
	s_cbranch_vccnz .LBB0_483
	ds_read_b128 v[48:51], v68 offset:16
	ds_read_b128 v[52:55], v68 offset:4112
.LBB0_483:
	v_lshlrev_b64 v[42:43], 9, v[66:67]
	v_lshl_add_u64 v[44:45], s[12:13], 0, v[42:43]
	s_waitcnt lgkmcnt(0)
	v_pk_mul_f32 v[42:43], v[34:35], v[54:55]
	v_pk_mul_f32 v[46:47], v[32:33], v[52:53]
	v_pk_mul_f32 v[34:35], v[34:35], v[50:51]
	v_pk_mul_f32 v[32:33], v[32:33], v[48:49]
	v_pk_fma_f32 v[42:43], v[38:39], v[50:51], v[42:43] neg_lo:[0,0,1] neg_hi:[0,0,1]
	v_pk_fma_f32 v[32:33], v[36:37], v[52:53], v[32:33]
	v_pk_fma_f32 v[34:35], v[38:39], v[54:55], v[34:35]
	v_pk_mul_f32 v[42:43], v[72:73], v[42:43]
	v_pk_mul_f32 v[34:35], v[72:73], v[34:35]
	v_pk_mul_f32 v[32:33], v[180:181], v[32:33]
	s_lshl_b32 s0, s53, 1
	s_mov_b32 s1, s43
	v_cvt_pk_bf16_f32 v59, v42, v43
	v_cvt_pk_bf16_f32 v42, v32, v33
	v_cvt_pk_bf16_f32 v43, v34, v35
	v_lshl_add_u64 v[32:33], v[44:45], 0, s[0:1]
	v_lshlrev_b32_e32 v34, 1, v156
	v_mov_b32_e32 v35, v161
	v_pk_fma_f32 v[46:47], v[36:37], v[48:49], v[46:47] neg_lo:[0,0,1] neg_hi:[0,0,1]
	v_lshl_add_u64 v[32:33], v[32:33], 0, v[34:35]
	v_lshlrev_b32_e32 v34, 1, v154
	v_pk_mul_f32 v[46:47], v[180:181], v[46:47]
	v_lshl_add_u64 v[32:33], v[32:33], 0, v[34:35]
	v_cvt_pk_bf16_f32 v58, v46, v47
	global_store_dwordx4 v[32:33], v[56:59], off
	global_store_dwordx4 v[32:33], v[40:43], off offset:32

; __device__ __forceinline__ u32x2 pack4(f32x4 v) { u32x2 w; w.x = cvt_pk_bf16(v[0], v[1]); w.y = cvt_pk_bf16(v[2], v[3]); return w; }
;     __device__ __forceinline__ void operator()(const Acc& acc, const pg8::Unit& u, int wr, int wc, int fr, int fq) const {
;     ...
;                     const int ax = fq >> 1, fh = fq & 1;
;                     u32x4 w1, w2;
; #pragma unroll
;                     for (int bj = 0; bj < 2; ++bj) {
;                         f32x4 cs = {1.f, 1.f, 1.f, 1.f}, sn = {0.f, 0.f, 0.f, 0.f};
;                         if (lat) { const int pidx = ax ? (t & 63) : (t >> 6); cs = *(const f32x4*)(rope + pidx * 16 + 8 * fh + 4 * bj); sn = *(const f32x4*)(rope + 1024 + pidx * 16 + 8 * fh + 4 * bj); }
;                         const f32x4 x1 = acc[ai][bj][m][0], x2 = acc[ai][bj][m][1];
;                         const u32x2 p1 = pack4((x1 * cs - x2 * sn) * scale), p2 = pack4((x2 * cs + x1 * sn) * scale);
;                         if (bj == 0) { w1.x = p1.x; w1.y = p1.y; w2.x = p2.x; w2.y = p2.y; } else { w1.z = p1.x; w1.w = p1.y; w2.z = p2.x; w2.w = p2.y; }
;                     }
;                     bf16_t* dq = dst + wc * 64 + ax * 32 + 8 * fh;
;                     *(u32x4*)dq = w1; *(u32x4*)(dq + 16) = w2;
.LBB0_519:
	v_lshrrev_b32_e32 v32, 6, v42
	v_cndmask_b32_e64 v32, v157, v32, s[14:15]
	v_lshlrev_b32_e32 v32, 6, v32
	v_mov_b32_e32 v33, v161
	v_lshl_add_u64 v[52:53], v[172:173], 0, v[32:33]
	v_subrev_u32_e32 v52, s100, v52
	v_add_u32_e32 v52, 0x20000, v52
	v_lshl_add_u64 v[54:55], v[174:175], 0, v[32:33]
	v_cndmask_b32_e64 v33, 0, 1, s[6:7]
	v_mov_b32_e32 v32, 1.0
	v_mov_b32_e32 v36, 0
	v_cmp_ne_u32_e64 s[0:1], 1, v33
	s_andn2_b64 vcc, exec, s[6:7]
	v_mov_b32_e32 v42, 0
	v_mov_b32_e32 v43, 0
	v_mov_b32_e32 v44, 0
	v_mov_b32_e32 v45, 0
	v_mov_b32_e32 v46, 1.0
	v_mov_b32_e32 v47, 1.0
	v_mov_b32_e32 v48, 1.0
	v_mov_b32_e32 v49, 1.0
	s_cbranch_vccnz .LBB0_521
	ds_read_b128 v[46:49], v52
	ds_read_b128 v[42:45], v52 offset:4096
.LBB0_521:
	s_waitcnt lgkmcnt(0)
	v_pk_mul_f32 v[34:35], v[26:27], v[44:45]
	v_pk_mul_f32 v[38:39], v[24:25], v[42:43]
	v_pk_fma_f32 v[34:35], v[30:31], v[48:49], v[34:35] neg_lo:[0,0,1] neg_hi:[0,0,1]
	v_pk_fma_f32 v[38:39], v[28:29], v[46:47], v[38:39] neg_lo:[0,0,1] neg_hi:[0,0,1]
	v_mov_b32_e32 v56, v180
	v_mov_b32_e32 v57, v180
	v_pk_mul_f32 v[24:25], v[24:25], v[46:47]
	v_pk_mul_f32 v[34:35], v[56:57], v[34:35]
	v_pk_mul_f32 v[38:39], v[180:181], v[38:39]
	v_pk_mul_f32 v[26:27], v[26:27], v[48:49]
	v_pk_fma_f32 v[24:25], v[28:29], v[42:43], v[24:25]
	v_cvt_pk_bf16_f32 v40, v38, v39
	v_cvt_pk_bf16_f32 v41, v34, v35
	v_pk_fma_f32 v[26:27], v[30:31], v[44:45], v[26:27]
	v_pk_mul_f32 v[24:25], v[180:181], v[24:25]
	s_and_b64 vcc, exec, s[0:1]
	v_mov_b32_e32 v37, 0
	v_mov_b32_e32 v38, 0
	v_mov_b32_e32 v39, 0
	v_mov_b32_e32 v33, 1.0
	v_mov_b32_e32 v34, 1.0
	v_mov_b32_e32 v35, 1.0
	v_pk_mul_f32 v[26:27], v[56:57], v[26:27]
	v_cvt_pk_bf16_f32 v24, v24, v25
	s_nop 0
	v_cvt_pk_bf16_f32 v25, v26, v27
	s_cbranch_vccnz .LBB0_523
	ds_read_b128 v[32:35], v52 offset:16
	ds_read_b128 v[36:39], v52 offset:4112
.LBB0_523:
	v_lshlrev_b64 v[26:27], 9, v[50:51]
	v_lshl_add_u64 v[28:29], s[12:13], 0, v[26:27]
	s_waitcnt lgkmcnt(0)
	v_pk_mul_f32 v[26:27], v[18:19], v[38:39]
	v_pk_mul_f32 v[30:31], v[16:17], v[36:37]
	v_pk_mul_f32 v[18:19], v[18:19], v[34:35]
	v_pk_mul_f32 v[16:17], v[16:17], v[32:33]
	v_pk_fma_f32 v[26:27], v[22:23], v[34:35], v[26:27] neg_lo:[0,0,1] neg_hi:[0,0,1]
	v_pk_fma_f32 v[16:17], v[20:21], v[36:37], v[16:17]
	v_pk_fma_f32 v[18:19], v[22:23], v[38:39], v[18:19]
	v_pk_mul_f32 v[26:27], v[56:57], v[26:27]
	v_pk_mul_f32 v[18:19], v[56:57], v[18:19]
	v_pk_mul_f32 v[16:17], v[180:181], v[16:17]
	s_lshl_b32 s0, s53, 1
	s_mov_b32 s1, s43
	v_cvt_pk_bf16_f32 v43, v26, v27
	v_cvt_pk_bf16_f32 v26, v16, v17
	v_cvt_pk_bf16_f32 v27, v18, v19
	v_lshl_add_u64 v[16:17], v[28:29], 0, s[0:1]
	v_lshlrev_b32_e32 v18, 1, v156
	v_mov_b32_e32 v19, v161
	v_pk_fma_f32 v[30:31], v[20:21], v[32:33], v[30:31] neg_lo:[0,0,1] neg_hi:[0,0,1]
	v_lshl_add_u64 v[16:17], v[16:17], 0, v[18:19]
	v_lshlrev_b32_e32 v18, 1, v154
	v_pk_mul_f32 v[30:31], v[180:181], v[30:31]
	v_lshl_add_u64 v[16:17], v[16:17], 0, v[18:19]
	v_cvt_pk_bf16_f32 v42, v30, v31
	global_store_dwordx4 v[16:17], v[40:43], off
	global_store_dwordx4 v[16:17], v[24:27], off offset:32

; __device__ __forceinline__ u32x2 pack4(f32x4 v) { u32x2 w; w.x = cvt_pk_bf16(v[0], v[1]); w.y = cvt_pk_bf16(v[2], v[3]); return w; }
;     __device__ __forceinline__ void operator()(const Acc& acc, const pg8::Unit& u, int wr, int wc, int fr, int fq) const {
;     ...
;                     const int ax = fq >> 1, fh = fq & 1;
;                     u32x4 w1, w2;
; #pragma unroll
;                     for (int bj = 0; bj < 2; ++bj) {
;                         f32x4 cs = {1.f, 1.f, 1.f, 1.f}, sn = {0.f, 0.f, 0.f, 0.f};
;                         if (lat) { const int pidx = ax ? (t & 63) : (t >> 6); cs = *(const f32x4*)(rope + pidx * 16 + 8 * fh + 4 * bj); sn = *(const f32x4*)(rope + 1024 + pidx * 16 + 8 * fh + 4 * bj); }
;                         const f32x4 x1 = acc[ai][bj][m][0], x2 = acc[ai][bj][m][1];
;                         const u32x2 p1 = pack4((x1 * cs - x2 * sn) * scale), p2 = pack4((x2 * cs + x1 * sn) * scale);
;                         if (bj == 0) { w1.x = p1.x; w1.y = p1.y; w2.x = p2.x; w2.y = p2.y; } else { w1.z = p1.x; w1.w = p1.y; w2.z = p2.x; w2.w = p2.y; }
;                     }
;                     bf16_t* dq = dst + wc * 64 + ax * 32 + 8 * fh;
;                     *(u32x4*)dq = w1; *(u32x4*)(dq + 16) = w2;
.LBB0_560:
	v_lshrrev_b32_e32 v16, 6, v26
	v_cndmask_b32_e64 v16, v159, v16, s[14:15]
	v_lshlrev_b32_e32 v160, 6, v16
	v_cndmask_b32_e64 v17, 0, 1, s[6:7]
	v_lshl_add_u64 v[36:37], v[172:173], 0, v[160:161]
	v_subrev_u32_e32 v36, s100, v36
	v_add_u32_e32 v36, 0x20000, v36
	v_lshl_add_u64 v[38:39], v[174:175], 0, v[160:161]
	v_mov_b32_e32 v16, 1.0
	v_mov_b32_e32 v20, 0
	v_cmp_ne_u32_e64 s[0:1], 1, v17
	s_andn2_b64 vcc, exec, s[6:7]
	v_mov_b32_e32 v26, 0
	v_mov_b32_e32 v27, 0
	v_mov_b32_e32 v28, 0
	v_mov_b32_e32 v29, 0
	v_mov_b32_e32 v30, 1.0
	v_mov_b32_e32 v31, 1.0
	v_mov_b32_e32 v32, 1.0
	v_mov_b32_e32 v33, 1.0
	s_cbranch_vccnz .LBB0_562
	ds_read_b128 v[30:33], v36
	ds_read_b128 v[26:29], v36 offset:4096
.LBB0_562:
	s_waitcnt lgkmcnt(0)
	v_pk_mul_f32 v[18:19], v[10:11], v[28:29]
	v_pk_mul_f32 v[22:23], v[8:9], v[26:27]
	v_pk_fma_f32 v[18:19], v[14:15], v[32:33], v[18:19] neg_lo:[0,0,1] neg_hi:[0,0,1]
	v_pk_fma_f32 v[22:23], v[12:13], v[30:31], v[22:23] neg_lo:[0,0,1] neg_hi:[0,0,1]
	v_mov_b32_e32 v40, v180
	v_mov_b32_e32 v41, v180
	v_pk_mul_f32 v[8:9], v[8:9], v[30:31]
	v_pk_mul_f32 v[18:19], v[40:41], v[18:19]
	v_pk_mul_f32 v[22:23], v[180:181], v[22:23]
	v_pk_mul_f32 v[10:11], v[10:11], v[32:33]
	v_pk_fma_f32 v[8:9], v[12:13], v[26:27], v[8:9]
	v_cvt_pk_bf16_f32 v24, v22, v23
	v_cvt_pk_bf16_f32 v25, v18, v19
	v_pk_fma_f32 v[10:11], v[14:15], v[28:29], v[10:11]
	v_pk_mul_f32 v[8:9], v[180:181], v[8:9]
	s_and_b64 vcc, exec, s[0:1]
	v_mov_b32_e32 v21, 0
	v_mov_b32_e32 v22, 0
	v_mov_b32_e32 v23, 0
	v_mov_b32_e32 v17, 1.0
	v_mov_b32_e32 v18, 1.0
	v_mov_b32_e32 v19, 1.0
	v_pk_mul_f32 v[10:11], v[40:41], v[10:11]
	v_cvt_pk_bf16_f32 v8, v8, v9
	s_nop 0
	v_cvt_pk_bf16_f32 v9, v10, v11
	s_cbranch_vccnz .LBB0_564
	ds_read_b128 v[16:19], v36 offset:16
	ds_read_b128 v[20:23], v36 offset:4112
.LBB0_564:
	v_lshlrev_b64 v[10:11], 9, v[34:35]
	v_lshl_add_u64 v[12:13], s[8:9], 0, v[10:11]
	s_waitcnt lgkmcnt(0)
	v_pk_mul_f32 v[10:11], v[2:3], v[22:23]
	v_pk_mul_f32 v[14:15], v[0:1], v[20:21]
	v_pk_mul_f32 v[0:1], v[0:1], v[16:17]
	v_pk_fma_f32 v[10:11], v[6:7], v[18:19], v[10:11] neg_lo:[0,0,1] neg_hi:[0,0,1]
	v_pk_fma_f32 v[0:1], v[4:5], v[20:21], v[0:1]
	v_pk_mul_f32 v[10:11], v[40:41], v[10:11]
	v_pk_mul_f32 v[0:1], v[180:181], v[0:1]
	s_lshl_b32 s42, s53, 1
	v_cvt_pk_bf16_f32 v27, v10, v11
	v_cvt_pk_bf16_f32 v10, v0, v1
	v_lshl_add_u64 v[0:1], v[12:13], 0, s[42:43]
	v_lshlrev_b32_e32 v160, 1, v156
	v_pk_fma_f32 v[14:15], v[4:5], v[16:17], v[14:15] neg_lo:[0,0,1] neg_hi:[0,0,1]
	v_pk_mul_f32 v[2:3], v[2:3], v[18:19]
	v_lshl_add_u64 v[0:1], v[0:1], 0, v[160:161]
	v_lshlrev_b32_e32 v160, 1, v154
	v_pk_mul_f32 v[14:15], v[180:181], v[14:15]
	v_pk_fma_f32 v[2:3], v[6:7], v[22:23], v[2:3]
	v_cvt_pk_bf16_f32 v26, v14, v15
	v_lshl_add_u64 v[0:1], v[0:1], 0, v[160:161]
	v_pk_mul_f32 v[2:3], v[40:41], v[2:3]
	s_nop 0
	v_cvt_pk_bf16_f32 v11, v2, v3
	global_store_dwordx4 v[0:1], v[24:27], off
	global_store_dwordx4 v[0:1], v[8:11], off offset:32
	s_andn2_b64 vcc, exec, s[4:5]
	s_mov_b64 s[0:1], -1
	s_cbranch_vccnz .LBB0_237
